# p0a section order split by bit 3 of the workgroup id, so both orders are present on every XCD
# speedup vs baseline: 1.0036x; 1.0036x over previous
_ZN2mk6mk_fwdENS_4ArgsE:
	s_lshr_b32 s100, s2, 3
	s_and_b32 s100, s100, 1
	s_mov_b64 s[4:5], s[0:1]
	s_load_dwordx2 s[60:61], s[0:1], 0x130
	s_load_dword s3, s[0:1], 0x138
	s_load_dwordx2 s[62:63], s[4:5], 0x120
	s_add_u32 s6, s0, 0x130
	v_writelane_b32 v251, s0, 0
	v_and_b32_e32 v200, 0x3ff, v0
	s_addc_u32 s7, s1, 0
	v_writelane_b32 v251, s1, 1
	v_readfirstlane_b32 s4, v200
	v_cmp_gt_u32_e32 vcc, 16, v200
	s_and_saveexec_b64 s[0:1], vcc
	v_lshl_add_u32 v1, v200, 2, 0
	v_add_u32_e32 v1, 0x24000, v1
	v_mov_b32_e32 v2, 0
	ds_write_b32 v1, v2
	s_or_b64 exec, exec, s[0:1]
	s_waitcnt lgkmcnt(0)
	s_barrier
	s_getreg_b32 s0, hwreg(HW_REG_XCC_ID, 0, 4)
	s_and_b32 s5, s0, 15
	v_cmp_eq_u32_e64 s[96:97], 0, v200
	s_and_saveexec_b64 s[0:1], s[96:97]
	s_cbranch_execz .LBB7_5
	s_mov_b64 s[8:9], exec
	v_mbcnt_lo_u32_b32 v1, s8, 0
	v_mbcnt_hi_u32_b32 v1, s9, v1
	v_cmp_eq_u32_e32 vcc, 0, v1
	s_and_b64 s[10:11], exec, vcc
	s_mov_b64 exec, s[10:11]
	s_cbranch_execz .LBB7_5
	s_lshl_b32 s10, s5, 8
	s_bcnt1_i32_b64 s8, s[8:9]
	v_mov_b32_e32 v1, s10
	v_mov_b32_e32 v2, s8
	global_atomic_add v1, v2, s[62:63] offset:1024
